# g3 row sum-of-squares lane exchanges by v_permlane16/32_swap instead of ds_bpermute
# speedup vs baseline: 1.0131x; 1.0131x over previous
.LBB0_1215:
	v_mov_b32_e32 v104, s91
	v_cndmask_b32_e64 v103, v74, v104, s[40:41]
	v_cndmask_b32_e64 v74, v103, v74, s[42:43]
	v_cndmask_b32_e64 v75, 0, v75, s[42:43]
	v_cndmask_b32_e64 v76, v76, 0, s[44:45]
	v_cndmask_b32_e64 v77, v77, 0, s[46:47]
	v_cvt_pk_bf16_f32 v74, v74, v75
	v_cvt_pk_bf16_f32 v75, v76, v77
	v_cvt_pk_bf16_f32 v76, v87, v89
	v_add_u32_e32 v103, v0, v122
	v_cvt_pk_bf16_f32 v77, v86, v88
	v_add_u32_e32 v86, v103, v123
	v_add_u32_e32 v104, v103, v124
	v_add_u32_e32 v108, v103, v125
	v_add_u32_e32 v103, v103, v126
	v_add_u32_e32 v127, 0x4800, v86
	v_add_u32_e32 v132, 0x4800, v104
	v_add_u32_e32 v133, 0x4800, v108
	v_add_u32_e32 v103, 0x4800, v103
	ds_read2_b64 v[86:89], v127 offset1:4
	ds_read2_b64 v[104:107], v132 offset1:4
	ds_read2_b64 v[108:111], v133 offset1:4
	ds_read2_b64 v[128:131], v103 offset1:4
	s_waitcnt lgkmcnt(0)
	v_mfma_f32_16x16x32_bf16 v[86:89], v[86:89], v[74:77], 0
	s_lshl_b32 s10, s34, 9
	s_add_i32 s10, s10, 0
	s_add_i32 s10, s10, 0x1b000
	v_mfma_f32_16x16x32_bf16 v[104:107], v[104:107], v[74:77], 0
	v_mfma_f32_16x16x32_bf16 v[108:111], v[108:111], v[74:77], 0
	v_mfma_f32_16x16x32_bf16 v[74:77], v[128:131], v[74:77], 0
	v_cvt_pk_bf16_f32 v78, v78, v81
	v_cvt_pk_bf16_f32 v79, v79, v80
	v_cvt_pk_bf16_f32 v80, v82, v85
	v_cvt_pk_bf16_f32 v81, v83, v84
	ds_read2_b64 v[82:85], v127 offset0:8 offset1:12
	v_add_u32_e32 v127, v0, v124
	s_waitcnt lgkmcnt(0)
	v_mfma_f32_16x16x32_bf16 v[82:85], v[82:85], v[78:81], v[86:89]
	s_nop 2
	ds_read2_b64 v[86:89], v132 offset0:8 offset1:12
	v_add_u32_e32 v128, v0, v125
	s_waitcnt lgkmcnt(0)
	v_mfma_f32_16x16x32_bf16 v[86:89], v[86:89], v[78:81], v[104:107]
	s_nop 2
	ds_read2_b64 v[104:107], v133 offset0:8 offset1:12
	s_waitcnt lgkmcnt(0)
	v_mfma_f32_16x16x32_bf16 v[104:107], v[104:107], v[78:81], v[108:111]
	s_nop 2
	ds_read2_b64 v[108:111], v103 offset0:8 offset1:12
	v_add_u32_e32 v103, v0, v123
	v_add_u32_e32 v0, v0, v126
	s_waitcnt lgkmcnt(0)
	v_mfma_f32_16x16x32_bf16 v[74:77], v[108:111], v[78:81], v[74:77]
	ds_read_b128 v[78:81], v103 offset:36864
	s_waitcnt lgkmcnt(0)
	v_mfma_f32_16x16x32_bf16 v[78:81], v[78:81], v[70:73], v[82:85]
	s_nop 2
	ds_read_b128 v[82:85], v127 offset:36864
	s_waitcnt lgkmcnt(0)
	v_mfma_f32_16x16x32_bf16 v[86:89], v[82:85], v[70:73], v[86:89]
	ds_read_b128 v[82:85], v128 offset:36864
	s_waitcnt lgkmcnt(0)
	v_mfma_f32_16x16x32_bf16 v[104:107], v[82:85], v[70:73], v[104:107]
	ds_read_b128 v[82:85], v0 offset:36864
	s_waitcnt lgkmcnt(0)
	v_mfma_f32_16x16x32_bf16 v[108:111], v[82:85], v[70:73], v[74:77]
	ds_read_b128 v[70:73], v103 offset:36928
	s_waitcnt lgkmcnt(0)
	v_mfma_f32_16x16x32_bf16 v[82:85], v[70:73], v[66:69], v[78:81]
	ds_read_b128 v[70:73], v127 offset:36928
	s_nop 1
	ds_read_b128 v[78:81], v0 offset:36928
	s_nop 3
	v_mul_f32_e32 v0, v83, v83
	s_waitcnt lgkmcnt(0)
	v_mfma_f32_16x16x32_bf16 v[74:77], v[70:73], v[66:69], v[86:89]
	ds_read_b128 v[70:73], v128 offset:36928
	v_fmac_f32_e32 v0, v82, v82
	s_waitcnt lgkmcnt(0)
	v_mfma_f32_16x16x32_bf16 v[70:73], v[70:73], v[66:69], v[104:107]
	v_mfma_f32_16x16x32_bf16 v[66:69], v[78:81], v[66:69], v[108:111]
	v_mul_f32_e32 v78, v85, v85
	v_fmac_f32_e32 v78, v84, v84
	v_add_f32_e32 v0, v0, v78
	v_mul_f32_e32 v78, v75, v75
	v_mul_f32_e32 v79, v77, v77
	v_fmac_f32_e32 v78, v74, v74
	v_fmac_f32_e32 v79, v76, v76
	v_add_f32_e32 v78, v78, v79
	v_add_f32_e32 v0, v0, v78
	v_mul_f32_e32 v78, v71, v71
	v_mul_f32_e32 v79, v73, v73
	v_fmac_f32_e32 v78, v70, v70
	v_fmac_f32_e32 v79, v72, v72
	v_add_f32_e32 v78, v78, v79
	v_add_f32_e32 v0, v0, v78
	v_mul_f32_e32 v78, v67, v67
	v_mul_f32_e32 v79, v69, v69
	v_fmac_f32_e32 v78, v66, v66
	v_fmac_f32_e32 v79, v68, v68
	v_add_f32_e32 v78, v78, v79
	v_add_f32_e32 v0, v0, v78
	v_mov_b32_e32 v78, v0
	s_nop 1
	v_permlane16_swap_b32 v78, v78
	s_waitcnt lgkmcnt(0)
	v_add_f32_e32 v0, v0, v78
	v_mov_b32_e32 v78, v0
	s_nop 1
	v_permlane32_swap_b32 v78, v78
	s_and_saveexec_b64 s[84:85], s[48:49]
	s_cbranch_execz .LBB0_1217
	s_lshl_b32 s90, s88, 2
	s_add_i32 s90, s10, s90
	v_lshl_add_u32 v79, v93, 2, s90
	s_waitcnt lgkmcnt(0)
	v_add_f32_e32 v0, v0, v78
	ds_write_b32 v79, v0
